# v92 + slack workgroups prefetch the SSM MC table slices of their XCD at the end of phase 2
# baseline (speedup 1.0000x reference)
.LBB0_363:
	v_readlane_b32 s26, v254, 38
	v_readlane_b32 s36, v254, 40
	v_readlane_b32 s96, v254, 37
	v_readlane_b32 s27, v254, 39
	v_readlane_b32 s37, v254, 41
	s_and_b32 s98, s96, 7
	s_mul_i32 s98, s98, 0x280000
	s_lshr_b32 s99, s96, 3
	s_and_b32 s99, s99, 15
	s_mul_i32 s99, s99, 0x28000
	s_add_i32 s98, s98, s99
	s_add_u32 s100, s78, 0x1600000
	s_addc_u32 s101, s79, 0
	s_add_u32 s100, s100, s98
	s_addc_u32 s101, s101, 0
	v_and_b32_e32 v152, 0x3ff, v0
	v_lshlrev_b32_e32 v152, 7, v152
	global_load_dword v153, v152, s[100:101]
	s_add_u32 s100, s100, 0x10000
	s_addc_u32 s101, s101, 0
	global_load_dword v154, v152, s[100:101]
	s_add_u32 s100, s100, 0x10000
	s_addc_u32 s101, s101, 0
	global_load_dword v155, v152, s[100:101]
